# MoBA block selection: top-3 gate values per query extracted in registers (three max / first-index passes) instead of the O(n^2) LDS rank loops
# speedup vs baseline: 1.0133x; 1.0044x over previous
; __device__ void moba_item(const P& p, int bh, int qt, char* smem) {
;     ...
;     for (int nn = 0; nn < 4; ++nn) sGate[q * 16 + nb + nn] = gsum[nn];
;   }
;   __syncthreads();
;   if (tid < 64) {
;     unsigned m = 0;
;     for (int n = 0; n < qblk; ++n) {
;       const float gn = sGate[tid * 16 + n];
;       int rank = 0;
;       for (int mm = 0; mm < qblk; ++mm) {
;         const float gm = sGate[tid * 16 + mm];
;         rank += (gm > gn || (gm == gn && mm < n)) ? 1 : 0;
;       }
;       if (rank < 3) m |= 1u << n;
;     }
;     sMask[tid] = m;
;   }
.LBB0_595:
	s_or_b64 exec, exec, s[0:1]
	v_lshlrev_b32_e32 v0, 2, v0
	v_lshl_or_b32 v0, v93, 6, v0
	v_cmp_gt_i32_e32 vcc, 64, v2
	ds_write_b128 v0, v[20:23] offset:32768
	s_waitcnt lgkmcnt(0)
	s_barrier
	s_and_saveexec_b64 s[10:11], vcc
	s_cbranch_execz .LBB0_608
	v_lshlrev_b32_e32 v21, 6, v2
	v_add_u32_e32 v22, 0x8000, v21
	ds_read_b128 v[28:31], v22
	ds_read_b128 v[32:35], v22 offset:16
	ds_read_b128 v[36:39], v22 offset:32
	ds_read_b128 v[40:43], v22 offset:48
	v_mov_b32_e32 v20, 0
	s_waitcnt lgkmcnt(0)
	s_cmp_gt_u32 s41, 0
	s_cselect_b64 s[0:1], -1, 0
	v_cndmask_b32_e64 v28, v244, v28, s[0:1]
	s_cmp_gt_u32 s41, 1
	s_cselect_b64 s[6:7], -1, 0
	v_cndmask_b32_e64 v29, v244, v29, s[6:7]
	s_cmp_gt_u32 s41, 2
	s_cselect_b64 s[8:9], -1, 0
	v_cndmask_b32_e64 v30, v244, v30, s[8:9]
	s_cmp_gt_u32 s41, 3
	s_cselect_b64 s[26:27], -1, 0
	v_cndmask_b32_e64 v31, v244, v31, s[26:27]
	s_cmp_gt_u32 s41, 4
	s_cselect_b64 s[0:1], -1, 0
	v_cndmask_b32_e64 v32, v244, v32, s[0:1]
	s_cmp_gt_u32 s41, 5
	s_cselect_b64 s[6:7], -1, 0
	v_cndmask_b32_e64 v33, v244, v33, s[6:7]
	s_cmp_gt_u32 s41, 6
	s_cselect_b64 s[8:9], -1, 0
	v_cndmask_b32_e64 v34, v244, v34, s[8:9]
	s_cmp_gt_u32 s41, 7
	s_cselect_b64 s[26:27], -1, 0
	v_cndmask_b32_e64 v35, v244, v35, s[26:27]
	s_cmp_gt_u32 s41, 8
	s_cselect_b64 s[0:1], -1, 0
	v_cndmask_b32_e64 v36, v244, v36, s[0:1]
	s_cmp_gt_u32 s41, 9
	s_cselect_b64 s[6:7], -1, 0
	v_cndmask_b32_e64 v37, v244, v37, s[6:7]
	s_cmp_gt_u32 s41, 10
	s_cselect_b64 s[8:9], -1, 0
	v_cndmask_b32_e64 v38, v244, v38, s[8:9]
	s_cmp_gt_u32 s41, 11
	s_cselect_b64 s[26:27], -1, 0
	v_cndmask_b32_e64 v39, v244, v39, s[26:27]
	s_cmp_gt_u32 s41, 12
	s_cselect_b64 s[0:1], -1, 0
	v_cndmask_b32_e64 v40, v244, v40, s[0:1]
	s_cmp_gt_u32 s41, 13
	s_cselect_b64 s[6:7], -1, 0
	v_cndmask_b32_e64 v41, v244, v41, s[6:7]
	s_cmp_gt_u32 s41, 14
	s_cselect_b64 s[8:9], -1, 0
	v_cndmask_b32_e64 v42, v244, v42, s[8:9]
	s_cmp_gt_u32 s41, 15
	s_cselect_b64 s[26:27], -1, 0
	v_cndmask_b32_e64 v43, v244, v43, s[26:27]
	v_max3_f32 v44, v28, v29, v30
	v_max3_f32 v44, v44, v31, v32
	v_max3_f32 v44, v44, v33, v34
	v_max3_f32 v44, v44, v35, v36
	v_max3_f32 v44, v44, v37, v38
	v_max3_f32 v44, v44, v39, v40
	v_max3_f32 v44, v44, v41, v42
	v_max_f32_e32 v44, v44, v43
	v_mov_b32_e32 v45, 0
	v_cmp_eq_f32_e64 s[0:1], v43, v44
	v_cmp_eq_f32_e64 s[6:7], v42, v44
	v_cmp_eq_f32_e64 s[8:9], v41, v44
	v_cmp_eq_f32_e64 s[26:27], v40, v44
	v_cndmask_b32_e64 v45, v45, 15, s[0:1]
	v_cmp_eq_f32_e64 s[0:1], v39, v44
	v_cndmask_b32_e64 v45, v45, 14, s[6:7]
	v_cmp_eq_f32_e64 s[6:7], v38, v44
	v_cndmask_b32_e64 v45, v45, 13, s[8:9]
	v_cmp_eq_f32_e64 s[8:9], v37, v44
	v_cndmask_b32_e64 v45, v45, 12, s[26:27]
	v_cmp_eq_f32_e64 s[26:27], v36, v44
	v_cndmask_b32_e64 v45, v45, 11, s[0:1]
	v_cmp_eq_f32_e64 s[0:1], v35, v44
	v_cndmask_b32_e64 v45, v45, 10, s[6:7]
	v_cmp_eq_f32_e64 s[6:7], v34, v44
	v_cndmask_b32_e64 v45, v45, 9, s[8:9]
	v_cmp_eq_f32_e64 s[8:9], v33, v44
	v_cndmask_b32_e64 v45, v45, 8, s[26:27]
	v_cmp_eq_f32_e64 s[26:27], v32, v44
	v_cndmask_b32_e64 v45, v45, 7, s[0:1]
	v_cmp_eq_f32_e64 s[0:1], v31, v44
	v_cndmask_b32_e64 v45, v45, 6, s[6:7]
	v_cmp_eq_f32_e64 s[6:7], v30, v44
	v_cndmask_b32_e64 v45, v45, 5, s[8:9]
	v_cmp_eq_f32_e64 s[8:9], v29, v44
	v_cndmask_b32_e64 v45, v45, 4, s[26:27]
	v_cmp_eq_f32_e64 s[26:27], v28, v44
	v_cndmask_b32_e64 v45, v45, 3, s[0:1]
	v_cndmask_b32_e64 v45, v45, 2, s[6:7]
	v_cndmask_b32_e64 v45, v45, 1, s[8:9]
	v_cndmask_b32_e64 v45, v45, 0, s[26:27]
	v_lshlrev_b32_e64 v46, v45, 1
	v_or_b32_e32 v20, v20, v46
	v_cmp_eq_u32_e64 s[0:1], 0, v45
	v_cmp_eq_u32_e64 s[6:7], 1, v45
	v_cmp_eq_u32_e64 s[8:9], 2, v45
	v_cmp_eq_u32_e64 s[26:27], 3, v45
	v_cndmask_b32_e64 v28, v28, v244, s[0:1]
	v_cmp_eq_u32_e64 s[0:1], 4, v45
	v_cndmask_b32_e64 v29, v29, v244, s[6:7]
	v_cmp_eq_u32_e64 s[6:7], 5, v45
	v_cndmask_b32_e64 v30, v30, v244, s[8:9]
	v_cmp_eq_u32_e64 s[8:9], 6, v45
	v_cndmask_b32_e64 v31, v31, v244, s[26:27]
	v_cmp_eq_u32_e64 s[26:27], 7, v45
	v_cndmask_b32_e64 v32, v32, v244, s[0:1]
	v_cmp_eq_u32_e64 s[0:1], 8, v45
	v_cndmask_b32_e64 v33, v33, v244, s[6:7]
	v_cmp_eq_u32_e64 s[6:7], 9, v45
	v_cndmask_b32_e64 v34, v34, v244, s[8:9]
	v_cmp_eq_u32_e64 s[8:9], 10, v45
	v_cndmask_b32_e64 v35, v35, v244, s[26:27]
	v_cmp_eq_u32_e64 s[26:27], 11, v45
	v_cndmask_b32_e64 v36, v36, v244, s[0:1]
	v_cmp_eq_u32_e64 s[0:1], 12, v45
	v_cndmask_b32_e64 v37, v37, v244, s[6:7]
	v_cmp_eq_u32_e64 s[6:7], 13, v45
	v_cndmask_b32_e64 v38, v38, v244, s[8:9]
	v_cmp_eq_u32_e64 s[8:9], 14, v45
	v_cndmask_b32_e64 v39, v39, v244, s[26:27]
; __device__ void moba_item(const P& p, int bh, int qt, char* smem) {
;     ...
;   if (tid < 64) {
;     unsigned m = 0;
;     for (int n = 0; n < qblk; ++n) {
;       const float gn = sGate[tid * 16 + n];
;       int rank = 0;
;       for (int mm = 0; mm < qblk; ++mm) {
;         const float gm = sGate[tid * 16 + mm];
;         rank += (gm > gn || (gm == gn && mm < n)) ? 1 : 0;
;       }
;       if (rank < 3) m |= 1u << n;
;     }
;     sMask[tid] = m;
;   }
	v_cmp_eq_u32_e64 s[26:27], 15, v45
	v_cndmask_b32_e64 v40, v40, v244, s[0:1]
	v_cndmask_b32_e64 v41, v41, v244, s[6:7]
	v_cndmask_b32_e64 v42, v42, v244, s[8:9]
	v_cndmask_b32_e64 v43, v43, v244, s[26:27]
	v_max3_f32 v44, v28, v29, v30
	v_max3_f32 v44, v44, v31, v32
	v_max3_f32 v44, v44, v33, v34
	v_max3_f32 v44, v44, v35, v36
	v_max3_f32 v44, v44, v37, v38
	v_max3_f32 v44, v44, v39, v40
	v_max3_f32 v44, v44, v41, v42
	v_max_f32_e32 v44, v44, v43
	v_mov_b32_e32 v45, 0
	v_cmp_eq_f32_e64 s[0:1], v43, v44
	v_cmp_eq_f32_e64 s[6:7], v42, v44
	v_cmp_eq_f32_e64 s[8:9], v41, v44
	v_cmp_eq_f32_e64 s[26:27], v40, v44
	v_cndmask_b32_e64 v45, v45, 15, s[0:1]
	v_cmp_eq_f32_e64 s[0:1], v39, v44
	v_cndmask_b32_e64 v45, v45, 14, s[6:7]
	v_cmp_eq_f32_e64 s[6:7], v38, v44
	v_cndmask_b32_e64 v45, v45, 13, s[8:9]
	v_cmp_eq_f32_e64 s[8:9], v37, v44
	v_cndmask_b32_e64 v45, v45, 12, s[26:27]
	v_cmp_eq_f32_e64 s[26:27], v36, v44
	v_cndmask_b32_e64 v45, v45, 11, s[0:1]
	v_cmp_eq_f32_e64 s[0:1], v35, v44
	v_cndmask_b32_e64 v45, v45, 10, s[6:7]
	v_cmp_eq_f32_e64 s[6:7], v34, v44
	v_cndmask_b32_e64 v45, v45, 9, s[8:9]
	v_cmp_eq_f32_e64 s[8:9], v33, v44
	v_cndmask_b32_e64 v45, v45, 8, s[26:27]
	v_cmp_eq_f32_e64 s[26:27], v32, v44
	v_cndmask_b32_e64 v45, v45, 7, s[0:1]
	v_cmp_eq_f32_e64 s[0:1], v31, v44
	v_cndmask_b32_e64 v45, v45, 6, s[6:7]
	v_cmp_eq_f32_e64 s[6:7], v30, v44
	v_cndmask_b32_e64 v45, v45, 5, s[8:9]
	v_cmp_eq_f32_e64 s[8:9], v29, v44
	v_cndmask_b32_e64 v45, v45, 4, s[26:27]
	v_cmp_eq_f32_e64 s[26:27], v28, v44
	v_cndmask_b32_e64 v45, v45, 3, s[0:1]
	v_cndmask_b32_e64 v45, v45, 2, s[6:7]
	v_cndmask_b32_e64 v45, v45, 1, s[8:9]
	v_cndmask_b32_e64 v45, v45, 0, s[26:27]
	v_lshlrev_b32_e64 v46, v45, 1
	v_or_b32_e32 v20, v20, v46
	v_cmp_eq_u32_e64 s[0:1], 0, v45
	v_cmp_eq_u32_e64 s[6:7], 1, v45
	v_cmp_eq_u32_e64 s[8:9], 2, v45
	v_cmp_eq_u32_e64 s[26:27], 3, v45
	v_cndmask_b32_e64 v28, v28, v244, s[0:1]
	v_cmp_eq_u32_e64 s[0:1], 4, v45
	v_cndmask_b32_e64 v29, v29, v244, s[6:7]
	v_cmp_eq_u32_e64 s[6:7], 5, v45
	v_cndmask_b32_e64 v30, v30, v244, s[8:9]
	v_cmp_eq_u32_e64 s[8:9], 6, v45
	v_cndmask_b32_e64 v31, v31, v244, s[26:27]
	v_cmp_eq_u32_e64 s[26:27], 7, v45
	v_cndmask_b32_e64 v32, v32, v244, s[0:1]
	v_cmp_eq_u32_e64 s[0:1], 8, v45
	v_cndmask_b32_e64 v33, v33, v244, s[6:7]
	v_cmp_eq_u32_e64 s[6:7], 9, v45
	v_cndmask_b32_e64 v34, v34, v244, s[8:9]
	v_cmp_eq_u32_e64 s[8:9], 10, v45
	v_cndmask_b32_e64 v35, v35, v244, s[26:27]
	v_cmp_eq_u32_e64 s[26:27], 11, v45
	v_cndmask_b32_e64 v36, v36, v244, s[0:1]
	v_cmp_eq_u32_e64 s[0:1], 12, v45
	v_cndmask_b32_e64 v37, v37, v244, s[6:7]
	v_cmp_eq_u32_e64 s[6:7], 13, v45
	v_cndmask_b32_e64 v38, v38, v244, s[8:9]
	v_cmp_eq_u32_e64 s[8:9], 14, v45
	v_cndmask_b32_e64 v39, v39, v244, s[26:27]
	v_cmp_eq_u32_e64 s[26:27], 15, v45
	v_cndmask_b32_e64 v40, v40, v244, s[0:1]
	v_cndmask_b32_e64 v41, v41, v244, s[6:7]
	v_cndmask_b32_e64 v42, v42, v244, s[8:9]
	v_cndmask_b32_e64 v43, v43, v244, s[26:27]
	v_max3_f32 v44, v28, v29, v30
	v_max3_f32 v44, v44, v31, v32
	v_max3_f32 v44, v44, v33, v34
	v_max3_f32 v44, v44, v35, v36
	v_max3_f32 v44, v44, v37, v38
	v_max3_f32 v44, v44, v39, v40
	v_max3_f32 v44, v44, v41, v42
	v_max_f32_e32 v44, v44, v43
	v_mov_b32_e32 v45, 0
	v_cmp_eq_f32_e64 s[0:1], v43, v44
	v_cmp_eq_f32_e64 s[6:7], v42, v44
	v_cmp_eq_f32_e64 s[8:9], v41, v44
	v_cmp_eq_f32_e64 s[26:27], v40, v44
	v_cndmask_b32_e64 v45, v45, 15, s[0:1]
	v_cmp_eq_f32_e64 s[0:1], v39, v44
	v_cndmask_b32_e64 v45, v45, 14, s[6:7]
	v_cmp_eq_f32_e64 s[6:7], v38, v44
	v_cndmask_b32_e64 v45, v45, 13, s[8:9]
	v_cmp_eq_f32_e64 s[8:9], v37, v44
	v_cndmask_b32_e64 v45, v45, 12, s[26:27]
	v_cmp_eq_f32_e64 s[26:27], v36, v44
	v_cndmask_b32_e64 v45, v45, 11, s[0:1]
	v_cmp_eq_f32_e64 s[0:1], v35, v44
	v_cndmask_b32_e64 v45, v45, 10, s[6:7]
	v_cmp_eq_f32_e64 s[6:7], v34, v44
	v_cndmask_b32_e64 v45, v45, 9, s[8:9]
	v_cmp_eq_f32_e64 s[8:9], v33, v44
	v_cndmask_b32_e64 v45, v45, 8, s[26:27]
	v_cmp_eq_f32_e64 s[26:27], v32, v44
	v_cndmask_b32_e64 v45, v45, 7, s[0:1]
	v_cmp_eq_f32_e64 s[0:1], v31, v44
	v_cndmask_b32_e64 v45, v45, 6, s[6:7]
	v_cmp_eq_f32_e64 s[6:7], v30, v44
	v_cndmask_b32_e64 v45, v45, 5, s[8:9]
	v_cmp_eq_f32_e64 s[8:9], v29, v44
	v_cndmask_b32_e64 v45, v45, 4, s[26:27]
	v_cmp_eq_f32_e64 s[26:27], v28, v44
	v_cndmask_b32_e64 v45, v45, 3, s[0:1]
	v_cndmask_b32_e64 v45, v45, 2, s[6:7]
	v_cndmask_b32_e64 v45, v45, 1, s[8:9]
	v_cndmask_b32_e64 v45, v45, 0, s[26:27]
	v_lshlrev_b32_e64 v46, v45, 1
	v_or_b32_e32 v20, v20, v46
	s_lshl_b32 s0, 1, s41
	s_add_i32 s0, s0, -1
	v_and_b32_e32 v20, s0, v20
